# grid barrier between m1 and m2 split into arrive/wait halves with the independent attention block executed in between
# baseline (speedup 1.0000x reference)
.LBB0_323:
	s_or_b64 exec, exec, s[8:9]
	v_cvt_f32_u32_e32 v4, v2
	s_waitcnt vmcnt(0)
	v_readfirstlane_b32 s6, v3
	v_sub_u32_e32 v3, 0, v2
	v_rcp_iflag_f32_e32 v4, v4
	v_add_u32_e32 v5, s6, v1
	v_mul_f32_e32 v4, 0x4f7ffffe, v4
	v_cvt_u32_f32_e32 v4, v4
	v_mul_lo_u32 v1, v3, v4
	v_mul_hi_u32 v1, v4, v1
	v_add_u32_e32 v1, v4, v1
	v_mul_hi_u32 v1, v5, v1
	v_mul_lo_u32 v3, v1, v2
	v_sub_u32_e32 v3, v5, v3
	v_add_u32_e32 v4, 1, v1
	v_cmp_ge_u32_e32 vcc, v3, v2
	s_nop 1
	v_cndmask_b32_e32 v1, v1, v4, vcc
	v_sub_u32_e32 v4, v3, v2
	v_cndmask_b32_e32 v3, v3, v4, vcc
	v_add_u32_e32 v4, 1, v1
	v_cmp_ge_u32_e32 vcc, v3, v2
	v_add_u32_e32 v3, 1, v5
	s_nop 0
	v_cndmask_b32_e32 v1, v1, v4, vcc
	v_mul_lo_u32 v4, v2, v1
	v_add_u32_e32 v2, v4, v2
	v_cmp_ne_u32_e32 vcc, v3, v2
	s_and_saveexec_b64 s[6:7], vcc
	s_xor_b64 s[6:7], exec, s[6:7]
	s_cbranch_execz .LBB0_337
	v_readfirstlane_b32 s98, v1
	s_mov_b32 s99, 0

.LBB0_340:
	s_or_b64 exec, exec, s[8:9]
	s_waitcnt vmcnt(0)
	v_readfirstlane_b32 s6, v2
	v_cvt_f32_u32_e32 v2, v0
	v_sub_u32_e32 v3, 0, v0
	v_add_u32_e32 v1, s6, v1
	s_add_u32 s6, s2, 0x7500
	v_rcp_iflag_f32_e32 v2, v2
	s_addc_u32 s7, s3, 0
	s_mov_b64 s[10:11], -1
	v_mul_f32_e32 v2, 0x4f7ffffe, v2
	v_cvt_u32_f32_e32 v2, v2
	v_mul_lo_u32 v3, v3, v2
	v_mul_hi_u32 v3, v2, v3
	v_add_u32_e32 v2, v2, v3
	v_mul_hi_u32 v2, v1, v2
	v_mul_lo_u32 v3, v2, v0
	v_sub_u32_e32 v3, v1, v3
	v_cmp_ge_u32_e32 vcc, v3, v0
	v_add_u32_e32 v4, 1, v2
	v_add_u32_e32 v1, 1, v1
	v_cndmask_b32_e32 v2, v2, v4, vcc
	v_sub_u32_e32 v4, v3, v0
	v_cndmask_b32_e32 v3, v3, v4, vcc
	v_cmp_ge_u32_e32 vcc, v3, v0
	v_add_u32_e32 v3, 1, v2
	s_nop 0
	v_cndmask_b32_e32 v2, v2, v3, vcc
	v_mul_lo_u32 v3, v0, v2
	v_add_u32_e32 v0, v3, v0
	v_cmp_ne_u32_e32 vcc, v1, v0
	v_mov_b64_e32 v[0:1], s[6:7]
	v_readfirstlane_b32 s98, v2
	s_mov_b32 s99, 2
	s_nop 1
	s_cbranch_vccz .Ls3_last
	s_mov_b32 s99, 1
	s_branch .Ls3_arr_end
.Ls3_last:
	global_atomic_add v[0:1], v199, off
	s_waitcnt vmcnt(0)
.Ls3_arr_end:
	s_or_b64 exec, exec, s[0:1]
	v_lshrrev_b32_e32 v0, 6, v194
	v_lshlrev_b32_e32 v0, 7, v0
	v_add_u32_e32 v0, 0x23000, v0
	v_mov_b32_e32 v1, s57
	ds_write_b32 v0, v1
	v_mov_b32_e32 v1, s58
	ds_write_b32 v0, v1 offset:4
	v_mov_b32_e32 v1, s59
	ds_write_b32 v0, v1 offset:8
	v_mov_b32_e32 v1, s60
	ds_write_b32 v0, v1 offset:12
	v_mov_b32_e32 v1, s61
	ds_write_b32 v0, v1 offset:16
	v_mov_b32_e32 v1, s62
	ds_write_b32 v0, v1 offset:20
	v_mov_b32_e32 v1, s63
	ds_write_b32 v0, v1 offset:24
	v_mov_b32_e32 v1, s64
	ds_write_b32 v0, v1 offset:28
	v_mov_b32_e32 v1, s65
	ds_write_b32 v0, v1 offset:32
	v_mov_b32_e32 v1, s66
	ds_write_b32 v0, v1 offset:36
	v_mov_b32_e32 v1, s67
	ds_write_b32 v0, v1 offset:40
	v_mov_b32_e32 v1, s68
	ds_write_b32 v0, v1 offset:44
	v_mov_b32_e32 v1, s69
	ds_write_b32 v0, v1 offset:48
	v_mov_b32_e32 v1, s70
	ds_write_b32 v0, v1 offset:52
	v_mov_b32_e32 v1, s71
	ds_write_b32 v0, v1 offset:56
	v_mov_b32_e32 v1, s72
	ds_write_b32 v0, v1 offset:60
	v_mov_b32_e32 v1, s73
	ds_write_b32 v0, v1 offset:64
	v_mov_b32_e32 v1, s74
	ds_write_b32 v0, v1 offset:68
	v_mov_b32_e32 v1, s75
	ds_write_b32 v0, v1 offset:72
	v_mov_b32_e32 v1, s76
	ds_write_b32 v0, v1 offset:76
	v_mov_b32_e32 v1, s77
	ds_write_b32 v0, v1 offset:80
	v_mov_b32_e32 v1, s78
	ds_write_b32 v0, v1 offset:84
	v_mov_b32_e32 v1, s79
	ds_write_b32 v0, v1 offset:88
	v_mov_b32_e32 v1, s80
	ds_write_b32 v0, v1 offset:92
	v_mov_b32_e32 v1, s81
	ds_write_b32 v0, v1 offset:96
	v_mov_b32_e32 v1, s82
	ds_write_b32 v0, v1 offset:100
	v_mov_b32_e32 v1, s83
	ds_write_b32 v0, v1 offset:104
	v_mov_b32_e32 v1, s84
	ds_write_b32 v0, v1 offset:108
	v_mov_b32_e32 v1, s85
	ds_write_b32 v0, v1 offset:112
	v_mov_b32_e32 v1, s86
	ds_write_b32 v0, v1 offset:116
	s_waitcnt lgkmcnt(0)
	s_branch .LBB0_494
.Lsync3_wait:
	s_and_saveexec_b64 s[0:1], s[74:75]
	s_cbranch_execz .LBB0_357
	s_load_dwordx2 s[2:3], s[72:73], 0x88
	s_getreg_b32 s4, hwreg(HW_REG_XCC_ID, 0, 4)
	s_and_b32 s33, s4, 15
	s_waitcnt lgkmcnt(0)
	s_lshl_b32 s4, s33, 8
	s_add_u32 s4, s2, s4
	s_addc_u32 s5, s3, 0
	s_add_u32 s4, s4, 0x4000
	s_addc_u32 s5, s5, 0
	s_mov_b32 s24, 0
	s_cmp_eq_u32 s99, 0
	s_cbranch_scc0 .Ls3w_leader
	s_add_u32 s12, s4, 0x2400
	s_addc_u32 s13, s5, 0
.Ls3w_nl:
	global_load_dword v0, v172, s[12:13] sc1
	s_waitcnt vmcnt(0)
	v_readfirstlane_b32 s6, v0
	s_cmp_lg_u32 s6, s98
	s_cbranch_scc1 .Ls3w_inv
	s_sleep 1
	s_add_i32 s24, s24, 1
	s_cmp_lt_u32 s24, 0x40001
	s_cbranch_scc1 .Ls3w_nl
.Ls3w_inv:
	buffer_inv sc1
	s_waitcnt vmcnt(0)
	s_branch .LBB0_357
.Ls3w_leader:
	s_cmp_eq_u32 s99, 2
	s_cbranch_scc1 .Ls3w_rel
	s_add_u32 s6, s2, 0x7500
	s_addc_u32 s7, s3, 0
.Ls3w_l:
	global_load_dword v0, v172, s[6:7] sc1
	s_waitcnt vmcnt(0)
	v_readfirstlane_b32 s8, v0
	s_cmp_lg_u32 s8, s98
	s_cbranch_scc1 .Ls3w_rel
	s_sleep 1
	s_add_i32 s24, s24, 1
	s_cmp_lt_u32 s24, 0x40001
	s_cbranch_scc1 .Ls3w_l
.Ls3w_rel:
	buffer_inv sc1
	v_mov_b32_e32 v0, 1
	v_mov_b32_e32 v1, 0x2000
	global_atomic_add v1, v0, s[4:5] offset:1024
	s_waitcnt vmcnt(0)

.Latt_done:
	v_lshrrev_b32_e32 v0, 6, v194
	v_lshlrev_b32_e32 v0, 7, v0
	v_add_u32_e32 v0, 0x23000, v0
	ds_read_b32 v1, v0
	ds_read_b32 v2, v0 offset:4
	ds_read_b32 v3, v0 offset:8
	ds_read_b32 v4, v0 offset:12
	ds_read_b32 v5, v0 offset:16
	ds_read_b32 v6, v0 offset:20
	ds_read_b32 v7, v0 offset:24
	ds_read_b32 v8, v0 offset:28
	ds_read_b32 v9, v0 offset:32
	ds_read_b32 v10, v0 offset:36
	ds_read_b32 v11, v0 offset:40
	ds_read_b32 v12, v0 offset:44
	ds_read_b32 v13, v0 offset:48
	ds_read_b32 v14, v0 offset:52
	ds_read_b32 v15, v0 offset:56
	s_waitcnt lgkmcnt(0)
	v_readfirstlane_b32 s57, v1
	v_readfirstlane_b32 s58, v2
	v_readfirstlane_b32 s59, v3
	v_readfirstlane_b32 s60, v4
	v_readfirstlane_b32 s61, v5
	v_readfirstlane_b32 s62, v6
	v_readfirstlane_b32 s63, v7
	v_readfirstlane_b32 s64, v8
	v_readfirstlane_b32 s65, v9
	v_readfirstlane_b32 s66, v10
	v_readfirstlane_b32 s67, v11
	v_readfirstlane_b32 s68, v12
	v_readfirstlane_b32 s69, v13
	v_readfirstlane_b32 s70, v14
	v_readfirstlane_b32 s71, v15
	ds_read_b32 v1, v0 offset:60
	ds_read_b32 v2, v0 offset:64
	ds_read_b32 v3, v0 offset:68
	ds_read_b32 v4, v0 offset:72
	ds_read_b32 v5, v0 offset:76
	ds_read_b32 v6, v0 offset:80
	ds_read_b32 v7, v0 offset:84
	ds_read_b32 v8, v0 offset:88
	ds_read_b32 v9, v0 offset:92
	ds_read_b32 v10, v0 offset:96
	ds_read_b32 v11, v0 offset:100
	ds_read_b32 v12, v0 offset:104
	ds_read_b32 v13, v0 offset:108
	ds_read_b32 v14, v0 offset:112
	ds_read_b32 v15, v0 offset:116
	s_waitcnt lgkmcnt(0)
	v_readfirstlane_b32 s72, v1
	v_readfirstlane_b32 s73, v2
	v_readfirstlane_b32 s74, v3
	v_readfirstlane_b32 s75, v4
	v_readfirstlane_b32 s76, v5
	v_readfirstlane_b32 s77, v6
	v_readfirstlane_b32 s78, v7
	v_readfirstlane_b32 s79, v8
	v_readfirstlane_b32 s80, v9
	v_readfirstlane_b32 s81, v10
	v_readfirstlane_b32 s82, v11
	v_readfirstlane_b32 s83, v12
	v_readfirstlane_b32 s84, v13
	v_readfirstlane_b32 s85, v14
	v_readfirstlane_b32 s86, v15
	s_nop 0
	s_branch .Lsync3_wait
